# in-proj phase start: rope table load issued without waiting; its LDS write happens after the GEMM prologue's first counted wait
# baseline (speedup 1.0000x reference)
; __device__ __forceinline__ int fresh_tid() { int t = threadIdx.x; asm volatile("" : "+v"(t)); return t; }
;     __host__ __device__ __forceinline__ bool next(int i, Unit& u) const { const long L = (long)i * G + cc; if (L >= nwg) return false; u.pm = (int)L / nN; u.pn = (int)L % nN; u.k0 = 0; u.nt = -1; u.flags = 0; return true; }
; template <class Epi, class Sched, bool ALIGN_EPI>
; __device__ __forceinline__ void gemm_phase(LAS unsigned char* lds, const Gemm g, const Sched& S, const Epi& E) {
;     const int tid = fresh_tid(), wid = __builtin_amdgcn_readfirstlane(tid >> 6), lane = tid & 63, wr = wid >> 2, wc = wid & 3, fr = lane & 15, fq = lane >> 4;
;     const int K = g.K, nt = K / BK;
;     unsigned voffA[2], voffB[2];
; #pragma unroll
;     for (int i = 0; i < 2; ++i) { int R, C; stage_rc(tid * 16 + i * 8192, R, C);
;         const int Rb = Epi::PERM ? ((R & ~31) + perm32(R & 31)) : R;
;         voffA[i] = (unsigned)(R * g.lda + C) * 2u; voffB[i] = (unsigned)(Rb * g.ldb + C) * 2u; }
;     const size_t kstep = (size_t)(BK * 2);
;     const size_t hstepA = (size_t)HALF * g.lda * 2, hstepB = (size_t)HALF * g.ldb * 2;
;     const size_t tstepA = 2 * hstepA, tstepB = 2 * hstepB;
;     const unsigned ldsw = (unsigned)wid * 1024u;
;     const int aoff = lds_byte(wr * 64 + fr, fq * 8), boff = lds_byte(wc * 32 + fr, fq * 8);
;     ...
;     Unit cur, nxt; int ui = 0;
;     if (!S.next(0, cur)) return;
;     f32x4 acc[2][2][4][2];
; #pragma unroll
;     for (int a = 0; a < 2; ++a)
; #pragma unroll
;         for (int b = 0; b < 2; ++b)
; #pragma unroll
;             for (int m = 0; m < 4; ++m)
; #pragma unroll
;                 for (int n = 0; n < 2; ++n) acc[a][b][m][n] = (f32x4){0.f, 0.f, 0.f, 0.f};
;     bf16x8 At[4][2], B0[2][2], B1[2][2];
;     const char* cA = (const char*)g.A + (size_t)cur.pm * tstepA + (size_t)cur.pn * g.a_pn_off * 2 + (size_t)cur.k0 * 2; const char* cB = (const char*)g.Bt + (size_t)cur.pn * tstepB + (size_t)cur.k0 * 2;
;     PG8_STAGE(PG8_SB(0, 0), cB, voffB); PG8_STAGE(PG8_SB(0, 1), cB + hstepB, voffB); PG8_STAGE(PG8_SA(0, 0), cA, voffA); PG8_STAGE(PG8_SA(0, 1), cA + hstepA, voffA);
;     if (wr == 1) PG8_BAR;
;     PG8_WAIT_V(2); PG8_BAR;
;     PG8_STAGE(PG8_SB(1, 0), cB + kstep, voffB); PG8_STAGE(PG8_SA(1, 0), cA + kstep, voffA); PG8_STAGE(PG8_SB(1, 1), cB + hstepB + kstep, voffB);
;     PG8_WAIT_V(6); PG8_BAR;
.LBB0_232:
	s_or_b64 exec, exec, s[0:1]
	s_mov_b32 s73, s43
	v_readlane_b32 s4, v254, 0
	v_mov_b32_e32 v7, v192
	v_readlane_b32 s5, v254, 1
	v_writelane_b32 v255, s72, 36
	s_waitcnt lgkmcnt(0)
	s_barrier
	v_readlane_b32 s100, v252, 4
	v_readlane_b32 s101, v252, 5
	v_lshlrev_b32_e32 v12, 4, v192
	s_add_u32 s100, s100, 0x40c0000
	s_addc_u32 s101, s101, 0
	s_nop 3
	global_load_dwordx4 v[248:251], v12, s[100:101]
	v_add_u32_e32 v246, 0x20000, v12
	s_and_b64 vcc, exec, s[4:5]
	v_readfirstlane_b32 s0, v7
	v_writelane_b32 v255, s73, 37
	s_cbranch_vccz .LBB0_616
	v_lshlrev_b32_e32 v0, 4, v7
	v_add_u32_e32 v1, 0x2000, v0
	v_ashrrev_i32_e32 v2, 31, v1
	v_lshrrev_b32_e32 v2, 22, v2
	v_add_u32_e32 v2, v1, v2
	v_ashrrev_i32_e32 v4, 10, v2
	v_mul_i32_i24_e32 v3, 0x400, v4
	v_sub_u32_e32 v1, v1, v3
	v_lshrrev_b32_e32 v3, 4, v1
	v_bitop3_b32 v1, v3, v1, 32 bitop3:0x6c
	v_ashrrev_i32_e32 v3, 31, v1
	v_lshrrev_b32_e32 v3, 26, v3
	v_add_u32_e32 v3, v1, v3
	v_ashrrev_i32_e32 v5, 6, v3
	v_and_b32_e32 v3, 0xc0, v3
	v_sub_u32_e32 v1, v1, v3
	v_lshlrev_b32_e32 v2, 5, v4
	v_ashrrev_i16_sdwa v1, v196, sext(v1) dst_sel:DWORD dst_unused:UNUSED_PAD src0_sel:DWORD src1_sel:BYTE_0
	v_and_b32_e32 v2, 32, v2
	v_bfe_i32 v6, v1, 0, 16
	v_add_u32_e32 v1, v2, v6
	v_lshlrev_b32_e32 v2, 3, v4
	v_and_b32_e32 v2, 0x1ffff0, v2
	v_add_lshl_u32 v2, v5, v2, 11
	v_lshl_add_u32 v146, v1, 1, v2
	v_bfe_i32 v2, v7, 27, 1
	v_lshrrev_b32_e32 v2, 22, v2
	v_add_u32_e32 v2, v0, v2
	v_and_b32_e32 v2, 0xfffffc00, v2
	v_sub_u32_e32 v0, v0, v2
	v_lshrrev_b32_e32 v2, 4, v0
	v_bitop3_b32 v2, v2, v0, 32 bitop3:0x6c
	v_ashrrev_i32_e32 v0, 31, v0
	v_lshrrev_b32_e32 v0, 26, v0
	v_ashrrev_i32_e32 v1, 31, v7
	v_add_u32_e32 v0, v2, v0
	v_lshrrev_b32_e32 v1, 26, v1
	v_ashrrev_i32_e32 v9, 6, v0
	v_readlane_b32 s4, v252, 0
	v_add_u32_e32 v1, v7, v1
	v_mul_i32_i24_e32 v0, 64, v9
	s_mul_i32 s1, s72, 0x500000
	v_readlane_b32 s8, v252, 4
	v_ashrrev_i32_e32 v8, 6, v1
	v_sub_u32_e32 v0, v2, v0
	v_readlane_b32 s9, v252, 5
	s_add_u32 s30, s8, s1
	v_lshlrev_b32_e32 v1, 5, v8
	v_ashrrev_i16_sdwa v0, v196, sext(v0) dst_sel:DWORD dst_unused:UNUSED_PAD src0_sel:DWORD src1_sel:BYTE_0
	v_readlane_b32 s6, v252, 2
	v_readlane_b32 s7, v252, 3
	s_addc_u32 s31, s9, 0
	s_ashr_i32 s4, s0, 6
	v_and_b32_e32 v1, 32, v1
	v_bfe_i32 v10, v0, 0, 16
	s_ashr_i32 s1, s0, 8
	s_lshl_b32 s38, s4, 10
	v_add_u32_e32 v0, v1, v10
	v_lshlrev_b32_e32 v1, 3, v8
	v_readlane_b32 s6, v254, 47
	v_and_b32_e32 v1, 0x1ffff0, v1
	v_readlane_b32 s7, v254, 48
	s_add_u32 s6, s30, s6
	v_add_lshl_u32 v1, v9, v1, 11
	s_addc_u32 s7, s31, s7
	s_add_i32 s39, s38, 0
	v_lshl_add_u32 v148, v0, 1, v1
	s_add_i32 m0, s39, 0x10000
	v_mov_b32_e32 v149, v161
	global_load_lds_dwordx4 v148, s[6:7]
	s_add_i32 m0, s39, 0x12000
	s_add_u32 s8, s6, 0x40000
	global_load_lds_dwordx4 v146, s[6:7]
	s_addc_u32 s9, s7, 0
	s_add_i32 m0, s39, 0x14000
	s_add_i32 s40, s39, 0x2000
	global_load_lds_dwordx4 v148, s[8:9]
	s_add_i32 m0, s39, 0x16000
	s_add_i32 s41, s39, 0x4000
	global_load_lds_dwordx4 v146, s[8:9]
	v_readlane_b32 s8, v254, 51
	s_mov_b32 m0, s39
	v_readlane_b32 s9, v254, 52
	s_add_i32 s75, s39, 0x6000
	v_mov_b32_e32 v147, v161
	s_cmp_eq_u32 s1, 1
	v_lshl_add_u64 v[0:1], s[6:7], 0, v[148:149]
	s_cselect_b64 s[46:47], -1, 0
	global_load_lds_dwordx4 v148, s[8:9]
	s_mov_b32 m0, s40
	s_cmp_lg_u32 s1, 1
	global_load_lds_dwordx4 v146, s[8:9]
	v_readlane_b32 s8, v254, 53
	s_mov_b32 m0, s41
	v_readlane_b32 s9, v254, 54
	v_lshl_add_u64 v[2:3], s[6:7], 0, v[146:147]
	v_readlane_b32 s5, v252, 1
	v_readlane_b32 s10, v252, 6
	v_readlane_b32 s11, v252, 7
	s_nop 0
	global_load_lds_dwordx4 v148, s[8:9]
	s_mov_b32 m0, s75
	s_nop 0
	global_load_lds_dwordx4 v146, s[8:9]
	s_cbranch_scc1 .LBB0_235
	s_barrier
.LBB0_235:
	v_readlane_b32 s12, v254, 51
	v_readlane_b32 s13, v254, 52
	s_and_b32 s8, s4, 3
	s_add_i32 m0, s39, 0x18000
	v_lshl_add_u64 v[0:1], v[0:1], 0, s[44:45]
	v_lshl_add_u64 v[12:13], s[12:13], 0, v[148:149]
	s_lshl_b32 s50, s1, 6
	s_lshl_b32 s1, s1, 13
	s_lshl_b32 s51, s8, 5
	s_lshl_b32 s9, s8, 12
	s_waitcnt vmcnt(2)
	ds_write_b128 v246, v[248:251]
	s_barrier
	global_load_lds_dwordx4 v[0:1], off
	v_lshl_add_u64 v[0:1], v[2:3], 0, s[44:45]
	s_add_i32 m0, s39, 0x1a000
	s_add_i32 s20, s39, 0x8000
	s_add_i32 s52, s39, 0xa000
	v_lshl_add_u64 v[14:15], s[12:13], 0, v[146:147]
	global_load_lds_dwordx4 v[0:1], off
	v_lshl_add_u64 v[0:1], v[12:13], 0, s[44:45]
	s_mov_b32 m0, s20
	s_add_u32 s4, s6, 0x40080
	global_load_lds_dwordx4 v[0:1], off
	v_lshl_add_u64 v[0:1], v[14:15], 0, s[44:45]
	s_mov_b32 m0, s52
	s_addc_u32 s5, s7, 0
	global_load_lds_dwordx4 v[0:1], off
	s_add_i32 m0, s39, 0x1c000
	v_lshl_add_u64 v[0:1], s[4:5], 0, v[148:149]
	global_load_lds_dwordx4 v[0:1], off
	v_lshl_add_u64 v[0:1], s[4:5], 0, v[146:147]
	s_add_i32 m0, s39, 0x1e000
	v_and_b32_e32 v151, 15, v7
	global_load_lds_dwordx4 v[0:1], off
	v_bfe_u32 v0, v7, 4, 2
	v_lshlrev_b32_e32 v150, 3, v0
	v_lshlrev_b32_e32 v1, 4, v0
	v_lshlrev_b32_e32 v3, 2, v7
	v_lshl_or_b32 v152, v0, 2, s51
	v_cmp_gt_u32_e64 s[14:15], 2, v0
	v_lshlrev_b32_e32 v0, 14, v8
	v_lshl_or_b32 v2, v151, 6, v1
	v_and_b32_e32 v3, 32, v3
	v_and_b32_e32 v0, 0xffff8000, v0
	v_bitop3_b32 v7, v2, s1, v3 bitop3:0xde
	s_cmpk_lt_u32 s0, 0x100
	v_and_b32_e32 v154, 8, v150
	v_and_b32_e32 v156, 32, v1
	v_readlane_b32 s0, v252, 14
	v_lshl_add_u32 v0, v9, 11, v0
	v_and_b32_e32 v1, 1, v8
	v_lshlrev_b32_e32 v160, 2, v154
	v_readlane_b32 s1, v252, 15
	v_lshl_or_b32 v0, v1, 6, v0
	v_lshl_add_u32 v176, v10, 1, v0
	v_lshl_add_u64 v[172:173], s[0:1], 0, v[160:161]
	v_readlane_b32 s0, v254, 2
	v_lshlrev_b32_e32 v0, 14, v4
	v_readlane_b32 s1, v254, 3
	v_and_b32_e32 v0, 0xffff8000, v0
	s_waitcnt vmcnt(6)
	v_lshl_add_u32 v0, v5, 11, v0
	v_lshl_add_u64 v[174:175], s[0:1], 0, v[160:161]
	v_and_b32_e32 v1, 1, v4
	v_readlane_b32 s0, v254, 49
	v_lshlrev_b32_e32 v158, 1, v152
	v_lshl_or_b32 v0, v1, 6, v0
	v_readlane_b32 s1, v254, 50
	v_bitop3_b32 v153, v2, s9, v3 bitop3:0xde
	s_cselect_b64 s[66:67], -1, 0
	s_lshl_b32 s53, s8, 6
	v_or_b32_e32 v155, 16, v151
	v_or_b32_e32 v157, 32, v151
	v_or_b32_e32 v159, 48, v151
	v_or_b32_e32 v166, 32, v158
	v_or_b32_e32 v168, 0x100, v158
	v_or_b32_e32 v170, 0x120, v158
	v_mov_b32_e32 v177, v161
	v_lshl_add_u32 v178, v6, 1, v0
	v_mov_b32_e32 v179, v161
	s_mov_b32 s54, 0
	v_add_u32_e32 v167, 0, v7
	v_readlane_b32 s55, v254, 46
	s_mov_b32 s10, s0
	s_mov_b64 s[0:1], s[12:13]
	s_barrier
	s_branch .LBB0_238
